# code placement: attention tile loop head aligned to 64 bytes (later GEMM clusters kept 8-byte aligned), on top of the aligned-cluster version
# baseline (speedup 1.0000x reference)
; template <bool FIRST> __device__ __forceinline__ void partialSM(f32x16& p0, f32x16& p1, float& m_ref, f32x16& negm, float& alpha) {
;     ...
;   alpha = 1.f;
;   if (FIRST || !__builtin_expect(__all(pmax <= THR2), 1)) {
;     const float dl = FIRST ? pmax : fmaxf(pmax, 0.f);
;     m_ref += dl; alpha = FIRST ? 1.f : __builtin_amdgcn_exp2f(-dl);
; #pragma unroll
;     for (int r = 0; r < 16; ++r) { p0[r] -= dl; p1[r] -= dl; }
; #pragma unroll
;     for (int r = 0; r < 16; ++r) negm[r] = -m_ref;
;     asm volatile("" : "+v"(negm));
;   }
; #pragma unroll
;   for (int r = 0; r < 16; ++r) p0[r] = __builtin_amdgcn_exp2f(p0[r]);
; __device__ __forceinline__ void attn_unit(const bf16_t* __restrict__ Qb, const bf16_t* __restrict__ KNh, const bf16_t* __restrict__ KRb, const bf16_t* __restrict__ Vh, ...
;   int tid_ = threadIdx.x; asm volatile("" : "+v"(tid_)); const int tid = tid_, wid = __builtin_amdgcn_readfirstlane(tid >> 6), lane = tid & 63, r32 = lane & 31, hi = lane >> 5;
;   bf16_t* V_lds = (bf16_t*)lds; bf16_t* K_lds = (bf16_t*)(lds + 3 * SHM_V);
;   float* ws = (float*)(lds + 3 * SHM_V + 3 * SHM_K) + wid * 64; float* al_l = ws + 32;
;   float m_ref = 0.f; f32x16 o[2] = {}; f32x16 osum = {}; f32x16 negm = {}; asm volatile("" : "+v"(negm)); bf16x8 qr[6];
;   const int srow = tid >> 3, sch = tid & 7, srow2 = tid >> 2, sch2 = tid & 3;
;   const bf16_t* kp = KNh + (long)srow * LDKN + 8 * sch; const bf16_t* vp = Vh + (long)srow * LDV + 8 * sch; const bf16_t* rp = KRb + (long)(srow2 & 63) * LDKR + 8 * sch2;
;   const int kst = KSWZ(srow, 16 * sch), vst = v_st(srow, 8 * sch), rst = KSWZ(srow2 & 63, 128 + 16 * sch2);
;   const bool has_r = wid < 4;
;   constexpr int BUF = SHM_V;
;   const int vb0 = (int)(uintptr_t)V_lds + v_rd_base(lane);
;   struct { bf16x8 v, k, r; } sr_[2];
;     ...
;   constexpr int SE = 0, SO = 1;
;   const int NT = seq / KVBLK;
;   SLOAD(SE, 0); SLOAD(SO, KVBLK);
;   const bf16_t* Qw = Qb + (long)(wid * QBLK + r32) * LDQ + hi * 8;
; #pragma unroll
;   for (int d0 = 0; d0 < 6; ++d0) qr[d0] = *reinterpret_cast<const bf16x8*>(Qw + d0 * 16);
;   {
;     const int pos = row_pos(qrow0 + wid * QBLK + r32); const float* cp = ropec + pos * 16 + 8 * hi; const float* sp = ropes + pos * 16 + 8 * hi;
;     unsigned w1[4], w2[4];
; #pragma unroll
;     for (int e = 0; e < 8; e += 2) { float o1[2], o2[2];
; #pragma unroll
.LBB0_721:
	s_and_b32 s8, s37, 0x3fffffc0
	v_and_b32_e32 v48, 63, v96
	s_lshl_b32 s8, s8, 2
	v_sub_f32_e32 v81, v17, v97
	s_add_i32 s29, s8, 0
	v_lshlrev_b32_e32 v17, 4, v48
	s_lshl_b32 s10, s36, 6
	s_ashr_i32 s31, s30, 31
	v_sub_f32_e32 v82, v18, v97
	v_sub_f32_e32 v80, v16, v97
	s_add_i32 s29, s29, 0x18000
	v_lshlrev_b32_e32 v16, 3, v48
	v_and_b32_e32 v17, 0xc0, v17
	v_lshlrev_b32_e32 v18, 1, v48
	v_and_or_b32 v17, v16, 24, v17
	v_and_b32_e32 v18, 32, v18
	v_and_b32_e32 v16, 0x100, v16
	s_cmp_lg_u32 0, -1
	v_or3_b32 v16, v17, v18, v16
	s_cselect_b32 s8, 0, 0
	s_mov_b32 s37, s11
	v_add_u32_e32 v203, s8, v16
	v_lshlrev_b32_e32 v16, 4, v96
	s_lshl_b64 s[36:37], s[36:37], 7
	v_sub_f32_e32 v32, v32, v97
	v_sub_f32_e32 v33, v33, v97
	v_sub_f32_e32 v34, v34, v97
	v_sub_f32_e32 v35, v35, v97
	v_sub_f32_e32 v36, v36, v97
	v_sub_f32_e32 v37, v37, v97
	v_sub_f32_e32 v38, v38, v97
	v_sub_f32_e32 v39, v39, v97
	v_sub_f32_e32 v40, v40, v97
	v_sub_f32_e32 v41, v41, v97
	v_sub_f32_e32 v42, v42, v97
	v_sub_f32_e32 v43, v43, v97
	v_sub_f32_e32 v44, v44, v97
	v_sub_f32_e32 v45, v45, v97
	v_sub_f32_e32 v46, v46, v97
	v_sub_f32_e32 v47, v47, v97
	v_and_b32_e32 v16, 0xfc0, v16
	v_mov_b32_e32 v17, v177
	s_add_u32 s36, s36, s38
	v_exp_f32_e32 v0, v32
	v_exp_f32_e32 v1, v33
	v_exp_f32_e32 v2, v34
	v_exp_f32_e32 v3, v35
	v_exp_f32_e32 v4, v36
	v_exp_f32_e32 v5, v37
	v_exp_f32_e32 v6, v38
	v_exp_f32_e32 v7, v39
	v_exp_f32_e32 v8, v40
	v_exp_f32_e32 v9, v41
	v_exp_f32_e32 v10, v42
	v_exp_f32_e32 v11, v43
	v_exp_f32_e32 v12, v44
	v_exp_f32_e32 v13, v45
	v_exp_f32_e32 v14, v46
	v_exp_f32_e32 v15, v47
	v_lshl_add_u64 v[16:17], s[40:41], 0, v[16:17]
	v_mov_b32_e32 v59, v177
	s_addc_u32 s37, s37, s39
	v_sub_f32_e32 v95, v31, v97
	v_sub_f32_e32 v94, v30, v97
	v_lshl_add_u64 v[178:179], v[16:17], 0, v[58:59]
	v_lshl_add_u64 v[180:181], s[36:37], 0, v[56:57]
	v_and_b32_e32 v16, 7, v96
	v_mov_b32_e32 v30, v177
	v_mov_b32_e32 v31, v177
	v_sub_f32_e32 v93, v29, v97
	v_sub_f32_e32 v92, v28, v97
	v_sub_f32_e32 v91, v27, v97
	v_sub_f32_e32 v90, v26, v97
	v_sub_f32_e32 v89, v25, v97
	v_sub_f32_e32 v88, v24, v97
	v_sub_f32_e32 v87, v23, v97
	v_sub_f32_e32 v86, v22, v97
	v_sub_f32_e32 v85, v21, v97
	v_sub_f32_e32 v84, v20, v97
	v_sub_f32_e32 v83, v19, v97
	v_cmp_gt_u32_e64 s[8:9], 32, v48
	v_lshl_or_b32 v180, v16, 4, v180
	v_mov_b32_e32 v16, v177
	v_mov_b32_e32 v17, v177
	v_mov_b32_e32 v18, v177
	v_mov_b32_e32 v19, v177
	v_mov_b32_e32 v20, v177
	v_mov_b32_e32 v21, v177
	v_mov_b32_e32 v22, v177
	v_mov_b32_e32 v23, v177
	v_mov_b32_e32 v24, v177
	v_mov_b32_e32 v25, v177
	v_mov_b32_e32 v26, v177
	v_mov_b32_e32 v27, v177
	v_mov_b32_e32 v28, v177
	v_mov_b32_e32 v29, v177
	v_mov_b64_e32 v[46:47], v[30:31]
	v_mov_b64_e32 v[62:63], v[30:31]
	s_mov_b32 s67, 4
	s_mov_b32 s77, 0
	v_lshl_add_u32 v192, v189, 2, s29
	s_movk_i32 s41, 0x4000
	s_mov_b32 s36, 0x8000
	v_mov_b64_e32 v[44:45], v[28:29]
	v_mov_b64_e32 v[42:43], v[26:27]
	v_mov_b64_e32 v[40:41], v[24:25]
	v_mov_b64_e32 v[38:39], v[22:23]
	v_mov_b64_e32 v[36:37], v[20:21]
	v_mov_b64_e32 v[34:35], v[18:19]
	v_mov_b64_e32 v[32:33], v[16:17]
	v_mov_b64_e32 v[60:61], v[28:29]
	v_mov_b64_e32 v[58:59], v[26:27]
	v_mov_b64_e32 v[56:57], v[24:25]
	v_mov_b64_e32 v[54:55], v[22:23]
	v_mov_b64_e32 v[52:53], v[20:21]
	v_mov_b64_e32 v[50:51], v[18:19]
	v_mov_b64_e32 v[48:49], v[16:17]
	s_waitcnt lgkmcnt(0)
	s_barrier
	.p2align	6

; #define PG8_WAIT_V(n) asm volatile("s_waitcnt vmcnt(" #n ")" ::: "memory")
; #define PG8_BAR __builtin_amdgcn_s_barrier()
; __device__ __forceinline__ unsigned xb_add(unsigned* p, unsigned v) { return __hip_atomic_fetch_add(p, v, __ATOMIC_RELAXED, __HIP_MEMORY_SCOPE_AGENT); }
; template <class Epi, class Sched, bool ALIGN_EPI = false, bool SP2 = false>
; __device__ __forceinline__ void gemm_phase(PG8_LAS unsigned char* lds, const Gemm g, const Sched& S, const Epi& E) {
;     ...
;     PG8_WAIT_V(0);
;     if constexpr (!ALIGN_EPI) { if (wr == 0) PG8_BAR; }
;     PG8_BAR;
; __device__ __forceinline__ void xcd_barrier(const XcdBarrier& b) {
;     asm volatile("s_waitcnt vmcnt(0)" ::: "memory");
;     __syncthreads();
;     if (threadIdx.x == 0) {
;         unsigned* bar = b.bar;
;         __builtin_amdgcn_s_waitcnt(0);
;         unsigned nloc = b.st[0], nx = b.st[1];
;         if (nloc == 0u) { xcd_barrier_complete(bar, b.x, nloc, nx); b.st[0] = nloc; b.st[1] = nx; }
;         const unsigned old = xb_add(&bar[XB_XSUB(b.x)], 1u);
.LBB0_760:
	s_nop 0
	s_setprio 0
	s_waitcnt vmcnt(0)
	s_barrier
	s_and_saveexec_b64 s[6:7], s[50:51]
	s_cbranch_execz .LBB0_812
	s_add_i32 s3, 0, 0x23fc0
	v_mov_b32_e32 v0, s3
	s_waitcnt vmcnt(0) expcnt(0) lgkmcnt(0)
	ds_read_b32 v2, v0
	s_add_i32 s3, 0, 0x23fc4
	v_mov_b32_e32 v0, s3
	ds_read_b32 v0, v0
	s_waitcnt lgkmcnt(1)
	v_cmp_ne_u32_e32 vcc, 0, v2
	s_cbranch_vccnz .LBB0_776
	v_readlane_b32 s8, v253, 0
	v_readlane_b32 s9, v253, 1
	s_mul_i32 s3, s9, s33
	s_mul_i32 s3, s3, s8
	s_add_u32 s8, s54, 0xc00200
	s_addc_u32 s9, s55, 0
	s_add_u32 s10, s54, 0xc00400
	s_addc_u32 s11, s55, 0
	s_add_u32 s12, s54, 0xc00500
	s_addc_u32 s13, s55, 0
	s_add_u32 s14, s54, 0xc00600
	s_addc_u32 s15, s55, 0
	s_add_u32 s16, s54, 0xc00700
	s_addc_u32 s17, s55, 0
	s_add_u32 s18, s54, 0xc00800
	s_addc_u32 s19, s55, 0
	s_add_u32 s20, s54, 0xc00900
	s_addc_u32 s21, s55, 0
	s_add_u32 s24, s54, 0xc00a00
	s_addc_u32 s25, s55, 0
	s_add_u32 s26, s54, 0xc00b00
	s_addc_u32 s27, s55, 0
	s_add_u32 s28, s54, 0xc00c00
	s_addc_u32 s29, s55, 0
	s_add_u32 s30, s54, 0xc00d00
	s_addc_u32 s31, s55, 0
	s_add_u32 s34, s54, 0xc00e00
	s_addc_u32 s35, s55, 0
	s_add_u32 s36, s54, 0xc00f00
	s_addc_u32 s37, s55, 0
	s_add_u32 s38, s54, 0xc01000
	s_addc_u32 s39, s55, 0
	s_add_u32 s40, s54, 0xc01100
	s_addc_u32 s41, s55, 0
	s_add_u32 s42, s54, 0xc01200
	s_addc_u32 s43, s55, 0
	s_add_u32 s44, s54, 0xc01300
	s_addc_u32 s45, s55, 0
	s_mov_b32 s58, 1
	v_mov_b32_e32 v16, 0
	s_branch .LBB0_764
